# baseline (speedup 1.0000x reference)
; __device__ __forceinline__ unsigned cvt_pk_bf16(float lo, float hi) { const f32x2 v = {lo, hi}; const bf16v2 r = __builtin_convertvector(v, bf16v2); return __builtin_bit_cast(unsigned, r); }
; __device__ __forceinline__ float bf_lo(unsigned u) { return __uint_as_float(u << 16); }
; __device__ __forceinline__ float bf_hi(unsigned u) { return __uint_as_float(u & 0xffff0000u); }
; __device__ __forceinline__ int otid() { int t = threadIdx.x; asm volatile("" : "+v"(t)); return t; }
; __device__ __forceinline__ int obid() { int b = blockIdx.x; asm volatile("" : "+s"(b)); return b; }
; __device__ void attn_combine(const bf16_t* AP, const float* LSE, bf16_t* MIX) {
;     ...
;     for (int i = obid() * 512 + otid(); i < n; i += gridDim.x * 512) {
;         const int tok = i >> 7, ch = i & 127, h = ch >> 4;
;         const float l0 = LSE[((size_t)0 * T + tok) * 8 + h], l1 = LSE[((size_t)1 * T + tok) * 8 + h], l2 = LSE[((size_t)2 * T + tok) * 8 + h];
;         const float m = fmaxf(l0, fmaxf(l1, l2)); float w0 = __expf(l0 - m), w1 = __expf(l1 - m), w2 = __expf(l2 - m); const float rs = 1.0f / (w0 + w1 + w2); w0 *= rs; w1 *= rs; w2 *= rs;
;         const u32x4 a = *(const u32x4*)(AP + ((size_t)0 * T + tok) * 1024 + ch * 8), b = *(const u32x4*)(AP + ((size_t)1 * T + tok) * 1024 + ch * 8), c = *(const u32x4*)(AP + ((size_t)2 * T + tok) * 1024 + ch * 8);
;         u32x4 w;
; #pragma unroll
;         for (int e = 0; e < 4; ++e) w[e] = cvt_pk_bf16(w0 * bf_lo(a[e]) + w1 * bf_lo(b[e]) + w2 * bf_lo(c[e]), w0 * bf_hi(a[e]) + w1 * bf_hi(b[e]) + w2 * bf_hi(c[e]));
;         *(u32x4*)(MIX + (size_t)tok * DM + ch * 8) = w;
.LBB0_297:
	v_ashrrev_i32_e32 v8, 7, v10
	v_ashrrev_i32_e32 v9, 31, v8
	v_lshlrev_b64 v[12:13], 5, v[8:9]
	s_mov_b64 s[4:5], 0x6000
	v_lshl_add_u64 v[12:13], v[2:3], 0, v[12:13]
	v_lshl_add_u64 v[16:17], v[8:9], 0, s[4:5]
	global_load_dword v0, v[12:13], off
	v_lshlrev_b64 v[12:13], 5, v[16:17]
	v_lshl_add_u64 v[12:13], v[2:3], 0, v[12:13]
	v_lshl_add_u64 v[20:21], v[8:9], 0, s[6:7]
	global_load_dword v11, v[12:13], off
	v_lshlrev_b64 v[12:13], 5, v[20:21]
	v_lshl_add_u64 v[12:13], v[2:3], 0, v[12:13]
	global_load_dword v12, v[12:13], off
	v_lshlrev_b64 v[20:21], 11, v[20:21]
	v_lshl_add_u64 v[20:21], v[4:5], 0, v[20:21]
	global_load_dwordx4 v[20:23], v[20:21], off
	v_lshlrev_b64 v[16:17], 11, v[16:17]
	v_lshl_add_u64 v[16:17], v[4:5], 0, v[16:17]
	v_lshlrev_b64 v[34:35], 11, v[8:9]
	v_lshl_add_u64 v[34:35], v[4:5], 0, v[34:35]
	global_load_dwordx4 v[36:39], v[34:35], off
	global_load_dwordx4 v[40:43], v[16:17], off
	v_add_u32_e32 v52, s67, v10
	v_cmp_gt_i32_e32 vcc, 0x300000, v52
	s_nop 1
	s_and_saveexec_b64 s[12:13], vcc
	v_ashrrev_i32_e32 v54, 7, v52
	v_ashrrev_i32_e32 v55, 31, v54
	v_lshlrev_b64 v[58:59], 5, v[54:55]
	s_mov_b64 s[4:5], 0x6000
	v_lshl_add_u64 v[58:59], v[2:3], 0, v[58:59]
	v_lshl_add_u64 v[62:63], v[54:55], 0, s[4:5]
	global_load_dword v50, v[58:59], off
	v_lshlrev_b64 v[58:59], 5, v[62:63]
	v_lshl_add_u64 v[58:59], v[2:3], 0, v[58:59]
	v_lshl_add_u64 v[66:67], v[54:55], 0, s[6:7]
	global_load_dword v57, v[58:59], off
	v_lshlrev_b64 v[58:59], 5, v[66:67]
	v_lshl_add_u64 v[58:59], v[2:3], 0, v[58:59]
	global_load_dword v58, v[58:59], off
	v_lshlrev_b64 v[66:67], 11, v[66:67]
	v_lshl_add_u64 v[66:67], v[4:5], 0, v[66:67]
	global_load_dwordx4 v[66:69], v[66:67], off
	v_lshlrev_b64 v[62:63], 11, v[62:63]
	v_lshl_add_u64 v[62:63], v[4:5], 0, v[62:63]
	v_lshlrev_b64 v[80:81], 11, v[54:55]
	v_lshl_add_u64 v[80:81], v[4:5], 0, v[80:81]
	global_load_dwordx4 v[82:85], v[80:81], off
	global_load_dwordx4 v[86:89], v[62:63], off
	s_mov_b64 exec, s[12:13]
	v_add_u32_e32 v98, s67, v52
	v_cmp_gt_i32_e32 vcc, 0x300000, v98
	s_nop 1
	s_and_saveexec_b64 s[12:13], vcc
	v_ashrrev_i32_e32 v100, 7, v98
	v_ashrrev_i32_e32 v101, 31, v100
	v_lshlrev_b64 v[104:105], 5, v[100:101]
	s_mov_b64 s[4:5], 0x6000
	v_lshl_add_u64 v[104:105], v[2:3], 0, v[104:105]
	v_lshl_add_u64 v[108:109], v[100:101], 0, s[4:5]
	global_load_dword v96, v[104:105], off
	v_lshlrev_b64 v[104:105], 5, v[108:109]
	v_lshl_add_u64 v[104:105], v[2:3], 0, v[104:105]
	v_lshl_add_u64 v[112:113], v[100:101], 0, s[6:7]
	global_load_dword v103, v[104:105], off
	v_lshlrev_b64 v[104:105], 5, v[112:113]
	v_lshl_add_u64 v[104:105], v[2:3], 0, v[104:105]
	global_load_dword v104, v[104:105], off
	v_lshlrev_b64 v[112:113], 11, v[112:113]
	v_lshl_add_u64 v[112:113], v[4:5], 0, v[112:113]
	global_load_dwordx4 v[112:115], v[112:113], off
	v_lshlrev_b64 v[108:109], 11, v[108:109]
	v_lshl_add_u64 v[108:109], v[4:5], 0, v[108:109]
	v_lshlrev_b64 v[126:127], 11, v[100:101]
	v_lshl_add_u64 v[126:127], v[4:5], 0, v[126:127]
	global_load_dwordx4 v[128:131], v[126:127], off
	global_load_dwordx4 v[132:135], v[108:109], off
	s_mov_b64 exec, s[12:13]
	v_add_u32_e32 v144, s67, v98
	v_cmp_gt_i32_e32 vcc, 0x300000, v144
	s_nop 1
	s_and_saveexec_b64 s[12:13], vcc
	v_ashrrev_i32_e32 v146, 7, v144
	v_ashrrev_i32_e32 v147, 31, v146
	v_lshlrev_b64 v[150:151], 5, v[146:147]
	s_mov_b64 s[4:5], 0x6000
	v_lshl_add_u64 v[150:151], v[2:3], 0, v[150:151]
	v_lshl_add_u64 v[154:155], v[146:147], 0, s[4:5]
	global_load_dword v142, v[150:151], off
	v_lshlrev_b64 v[150:151], 5, v[154:155]
	v_lshl_add_u64 v[150:151], v[2:3], 0, v[150:151]
	v_lshl_add_u64 v[158:159], v[146:147], 0, s[6:7]
	global_load_dword v149, v[150:151], off
	v_lshlrev_b64 v[150:151], 5, v[158:159]
	v_lshl_add_u64 v[150:151], v[2:3], 0, v[150:151]
	global_load_dword v150, v[150:151], off
	v_lshlrev_b64 v[158:159], 11, v[158:159]
	v_lshl_add_u64 v[158:159], v[4:5], 0, v[158:159]
	global_load_dwordx4 v[158:161], v[158:159], off
	v_lshlrev_b64 v[154:155], 11, v[154:155]
	v_lshl_add_u64 v[154:155], v[4:5], 0, v[154:155]
	v_lshlrev_b64 v[172:173], 11, v[146:147]
	v_lshl_add_u64 v[172:173], v[4:5], 0, v[172:173]
	global_load_dwordx4 v[174:177], v[172:173], off
	global_load_dwordx4 v[178:181], v[154:155], off
	s_mov_b64 exec, s[12:13]
	v_add_u32_e32 v10, s67, v144
	s_waitcnt vmcnt(21)
	v_max3_f32 v13, v0, v11, v12
	v_sub_f32_e32 v0, v0, v13
	v_mul_f32_e32 v0, 0x3fb8aa3b, v0
	v_exp_f32_e32 v25, v0
	v_sub_f32_e32 v0, v11, v13
	v_mul_f32_e32 v0, 0x3fb8aa3b, v0
	v_exp_f32_e32 v24, v0
	v_sub_f32_e32 v0, v12, v13
	v_mul_f32_e32 v0, 0x3fb8aa3b, v0
	v_exp_f32_e32 v11, v0
	v_add_f32_e32 v0, v25, v24
	s_waitcnt vmcnt(20)
	v_lshlrev_b32_e32 v32, 16, v20
	v_and_b32_e32 v33, 0xffff0000, v20
	v_add_f32_e32 v0, v11, v0
	v_div_scale_f32 v12, s[4:5], v0, v0, 1.0
	v_rcp_f32_e32 v13, v12
	v_lshlrev_b32_e32 v20, 16, v21
	v_and_b32_e32 v21, 0xffff0000, v21
	v_fma_f32 v14, -v12, v13, 1.0
	v_fmac_f32_e32 v13, v14, v13
	v_div_scale_f32 v14, vcc, 1.0, v0, 1.0
	v_mul_f32_e32 v15, v14, v13
	v_fma_f32 v18, -v12, v15, v14
	v_fmac_f32_e32 v15, v18, v13
	v_fma_f32 v12, -v12, v15, v14
	v_div_fmas_f32 v12, v12, v13, v15
	v_div_fixup_f32 v0, v12, v0, 1.0
	v_pk_mul_f32 v[24:25], v[24:25], v[0:1] op_sel_hi:[1,0]
	v_mul_f32_e32 v26, v11, v0
	v_lshlrev_b64 v[8:9], 12, v[8:9]
	v_lshl_add_u64 v[8:9], v[6:7], 0, v[8:9]
	s_waitcnt vmcnt(18)
	v_lshlrev_b32_e32 v30, 16, v36
	v_and_b32_e32 v29, 0xffff0000, v36
	s_waitcnt vmcnt(18)
; __device__ __forceinline__ unsigned cvt_pk_bf16(float lo, float hi) { const f32x2 v = {lo, hi}; const bf16v2 r = __builtin_convertvector(v, bf16v2); return __builtin_bit_cast(unsigned, r); }
; __device__ __forceinline__ float bf_lo(unsigned u) { return __uint_as_float(u << 16); }
; __device__ __forceinline__ float bf_hi(unsigned u) { return __uint_as_float(u & 0xffff0000u); }
; __device__ __forceinline__ int otid() { int t = threadIdx.x; asm volatile("" : "+v"(t)); return t; }
; __device__ __forceinline__ int obid() { int b = blockIdx.x; asm volatile("" : "+s"(b)); return b; }
; __device__ void attn_combine(const bf16_t* AP, const float* LSE, bf16_t* MIX) {
;     ...
;     for (int i = obid() * 512 + otid(); i < n; i += gridDim.x * 512) {
;         const int tok = i >> 7, ch = i & 127, h = ch >> 4;
;         const float l0 = LSE[((size_t)0 * T + tok) * 8 + h], l1 = LSE[((size_t)1 * T + tok) * 8 + h], l2 = LSE[((size_t)2 * T + tok) * 8 + h];
;         const float m = fmaxf(l0, fmaxf(l1, l2)); float w0 = __expf(l0 - m), w1 = __expf(l1 - m), w2 = __expf(l2 - m); const float rs = 1.0f / (w0 + w1 + w2); w0 *= rs; w1 *= rs; w2 *= rs;
;         const u32x4 a = *(const u32x4*)(AP + ((size_t)0 * T + tok) * 1024 + ch * 8), b = *(const u32x4*)(AP + ((size_t)1 * T + tok) * 1024 + ch * 8), c = *(const u32x4*)(AP + ((size_t)2 * T + tok) * 1024 + ch * 8);
;         u32x4 w;
; #pragma unroll
;         for (int e = 0; e < 4; ++e) w[e] = cvt_pk_bf16(w0 * bf_lo(a[e]) + w1 * bf_lo(b[e]) + w2 * bf_lo(c[e]), w0 * bf_hi(a[e]) + w1 * bf_hi(b[e]) + w2 * bf_hi(c[e]));
;         *(u32x4*)(MIX + (size_t)tok * DM + ch * 8) = w;
	v_and_b32_e32 v31, 0xffff0000, v40
	v_lshlrev_b32_e32 v28, 16, v40
	v_pk_mul_f32 v[30:31], v[24:25], v[30:31] op_sel:[1,0] op_sel_hi:[0,1]
	v_pk_fma_f32 v[28:29], v[24:25], v[28:29], v[30:31]
	v_lshlrev_b32_e32 v40, 16, v37
	v_pk_fma_f32 v[28:29], v[26:27], v[32:33], v[28:29] op_sel_hi:[0,1,1]
	v_cvt_pk_bf16_f32 v36, v28, v29
	v_lshlrev_b32_e32 v28, 16, v41
	v_and_b32_e32 v41, 0xffff0000, v41
	v_and_b32_e32 v29, 0xffff0000, v37
	v_pk_mul_f32 v[40:41], v[24:25], v[40:41] op_sel:[1,0] op_sel_hi:[0,1]
	v_pk_fma_f32 v[40:41], v[24:25], v[28:29], v[40:41]
	v_lshlrev_b32_e32 v28, 16, v22
	v_pk_fma_f32 v[40:41], v[26:27], v[20:21], v[40:41] op_sel_hi:[0,1,1]
	v_lshlrev_b32_e32 v20, 16, v38
	v_and_b32_e32 v21, 0xffff0000, v42
	v_cvt_pk_bf16_f32 v37, v40, v41
	v_lshlrev_b32_e32 v40, 16, v42
	v_and_b32_e32 v41, 0xffff0000, v38
	v_pk_mul_f32 v[20:21], v[24:25], v[20:21] op_sel:[1,0] op_sel_hi:[0,1]
	v_and_b32_e32 v29, 0xffff0000, v22
	v_pk_fma_f32 v[40:41], v[24:25], v[40:41], v[20:21]
	v_lshlrev_b32_e32 v42, 16, v39
	v_pk_fma_f32 v[40:41], v[26:27], v[28:29], v[40:41] op_sel_hi:[0,1,1]
	v_cvt_pk_bf16_f32 v38, v40, v41
	v_lshlrev_b32_e32 v40, 16, v43
	v_and_b32_e32 v43, 0xffff0000, v43
	v_and_b32_e32 v41, 0xffff0000, v39
	v_pk_mul_f32 v[42:43], v[24:25], v[42:43] op_sel:[1,0] op_sel_hi:[0,1]
	v_pk_fma_f32 v[40:41], v[24:25], v[40:41], v[42:43]
	v_lshlrev_b32_e32 v42, 16, v23
	v_and_b32_e32 v43, 0xffff0000, v23
	v_pk_fma_f32 v[40:41], v[26:27], v[42:43], v[40:41] op_sel_hi:[0,1,1]
	v_cvt_pk_bf16_f32 v39, v40, v41
	global_store_dwordx4 v[8:9], v[36:39], off
	s_waitcnt vmcnt(16)
	v_max3_f32 v59, v50, v57, v58
	v_sub_f32_e32 v50, v50, v59
	v_mul_f32_e32 v50, 0x3fb8aa3b, v50
	v_exp_f32_e32 v71, v50
	v_sub_f32_e32 v50, v57, v59
	v_mul_f32_e32 v50, 0x3fb8aa3b, v50
	v_exp_f32_e32 v70, v50
	v_sub_f32_e32 v50, v58, v59
	v_mul_f32_e32 v50, 0x3fb8aa3b, v50
	v_exp_f32_e32 v57, v50
	v_add_f32_e32 v50, v71, v70
	s_waitcnt vmcnt(15)
	v_lshlrev_b32_e32 v78, 16, v66
	v_and_b32_e32 v79, 0xffff0000, v66
	v_add_f32_e32 v50, v57, v50
	v_div_scale_f32 v58, s[4:5], v50, v50, 1.0
	v_rcp_f32_e32 v59, v58
	v_lshlrev_b32_e32 v66, 16, v67
	v_and_b32_e32 v67, 0xffff0000, v67
	v_fma_f32 v60, -v58, v59, 1.0
	v_fmac_f32_e32 v59, v60, v59
	v_div_scale_f32 v60, vcc, 1.0, v50, 1.0
	v_mul_f32_e32 v61, v60, v59
	v_fma_f32 v64, -v58, v61, v60
	v_fmac_f32_e32 v61, v64, v59
	v_fma_f32 v58, -v58, v61, v60
	v_div_fmas_f32 v58, v58, v59, v61
	v_div_fixup_f32 v50, v58, v50, 1.0
	v_pk_mul_f32 v[70:71], v[70:71], v[50:51] op_sel_hi:[1,0]
	v_mul_f32_e32 v72, v57, v50
	v_lshlrev_b64 v[54:55], 12, v[54:55]
	v_lshl_add_u64 v[54:55], v[6:7], 0, v[54:55]
	s_waitcnt vmcnt(13)
	v_lshlrev_b32_e32 v76, 16, v82
	v_and_b32_e32 v75, 0xffff0000, v82
	s_waitcnt vmcnt(13)
	v_and_b32_e32 v77, 0xffff0000, v86
	v_lshlrev_b32_e32 v74, 16, v86
	v_pk_mul_f32 v[76:77], v[70:71], v[76:77] op_sel:[1,0] op_sel_hi:[0,1]
	v_pk_fma_f32 v[74:75], v[70:71], v[74:75], v[76:77]
	v_lshlrev_b32_e32 v86, 16, v83
	v_pk_fma_f32 v[74:75], v[72:73], v[78:79], v[74:75] op_sel_hi:[0,1,1]
	v_cvt_pk_bf16_f32 v82, v74, v75
	v_lshlrev_b32_e32 v74, 16, v87
	v_and_b32_e32 v87, 0xffff0000, v87
	v_and_b32_e32 v75, 0xffff0000, v83
	v_pk_mul_f32 v[86:87], v[70:71], v[86:87] op_sel:[1,0] op_sel_hi:[0,1]
	v_pk_fma_f32 v[86:87], v[70:71], v[74:75], v[86:87]
	v_lshlrev_b32_e32 v74, 16, v68
	v_pk_fma_f32 v[86:87], v[72:73], v[66:67], v[86:87] op_sel_hi:[0,1,1]
	v_lshlrev_b32_e32 v66, 16, v84
	v_and_b32_e32 v67, 0xffff0000, v88
	v_cvt_pk_bf16_f32 v83, v86, v87
	v_lshlrev_b32_e32 v86, 16, v88
	v_and_b32_e32 v87, 0xffff0000, v84
	v_pk_mul_f32 v[66:67], v[70:71], v[66:67] op_sel:[1,0] op_sel_hi:[0,1]
	v_and_b32_e32 v75, 0xffff0000, v68
	v_pk_fma_f32 v[86:87], v[70:71], v[86:87], v[66:67]
	v_lshlrev_b32_e32 v88, 16, v85
	v_pk_fma_f32 v[86:87], v[72:73], v[74:75], v[86:87] op_sel_hi:[0,1,1]
	v_cvt_pk_bf16_f32 v84, v86, v87
	v_lshlrev_b32_e32 v86, 16, v89
	v_and_b32_e32 v89, 0xffff0000, v89
	v_and_b32_e32 v87, 0xffff0000, v85
	v_pk_mul_f32 v[88:89], v[70:71], v[88:89] op_sel:[1,0] op_sel_hi:[0,1]
	v_pk_fma_f32 v[86:87], v[70:71], v[86:87], v[88:89]
	v_lshlrev_b32_e32 v88, 16, v69
	v_and_b32_e32 v89, 0xffff0000, v69
	v_pk_fma_f32 v[86:87], v[72:73], v[88:89], v[86:87] op_sel_hi:[0,1,1]
	v_cvt_pk_bf16_f32 v85, v86, v87
	v_cmp_gt_i32_e32 vcc, 0x300000, v52
	s_nop 1
	s_and_saveexec_b64 s[12:13], vcc
	global_store_dwordx4 v[54:55], v[82:85], off
	s_mov_b64 exec, s[12:13]
	s_waitcnt vmcnt(11)
	v_max3_f32 v105, v96, v103, v104
	v_sub_f32_e32 v96, v96, v105
	v_mul_f32_e32 v96, 0x3fb8aa3b, v96
	v_exp_f32_e32 v117, v96
	v_sub_f32_e32 v96, v103, v105
	v_mul_f32_e32 v96, 0x3fb8aa3b, v96
	v_exp_f32_e32 v116, v96
	v_sub_f32_e32 v96, v104, v105
	v_mul_f32_e32 v96, 0x3fb8aa3b, v96
	v_exp_f32_e32 v103, v96
	v_add_f32_e32 v96, v117, v116
	s_waitcnt vmcnt(10)
	v_lshlrev_b32_e32 v124, 16, v112
	v_and_b32_e32 v125, 0xffff0000, v112
	v_add_f32_e32 v96, v103, v96
	v_div_scale_f32 v104, s[4:5], v96, v96, 1.0
	v_rcp_f32_e32 v105, v104
	v_lshlrev_b32_e32 v112, 16, v113
	v_and_b32_e32 v113, 0xffff0000, v113
	v_fma_f32 v106, -v104, v105, 1.0
	v_fmac_f32_e32 v105, v106, v105
	v_div_scale_f32 v106, vcc, 1.0, v96, 1.0
	v_mul_f32_e32 v107, v106, v105
	v_fma_f32 v110, -v104, v107, v106
	v_fmac_f32_e32 v107, v110, v105
	v_fma_f32 v104, -v104, v107, v106
	v_div_fmas_f32 v104, v104, v105, v107
	v_div_fixup_f32 v96, v104, v96, 1.0
	v_pk_mul_f32 v[116:117], v[116:117], v[96:97] op_sel_hi:[1,0]
	v_mul_f32_e32 v118, v103, v96
	v_lshlrev_b64 v[100:101], 12, v[100:101]
	v_lshl_add_u64 v[100:101], v[6:7], 0, v[100:101]
	s_waitcnt vmcnt(8)
; __device__ __forceinline__ unsigned cvt_pk_bf16(float lo, float hi) { const f32x2 v = {lo, hi}; const bf16v2 r = __builtin_convertvector(v, bf16v2); return __builtin_bit_cast(unsigned, r); }
; __device__ __forceinline__ float bf_lo(unsigned u) { return __uint_as_float(u << 16); }
; __device__ __forceinline__ float bf_hi(unsigned u) { return __uint_as_float(u & 0xffff0000u); }
; __device__ __forceinline__ int otid() { int t = threadIdx.x; asm volatile("" : "+v"(t)); return t; }
; __device__ __forceinline__ int obid() { int b = blockIdx.x; asm volatile("" : "+s"(b)); return b; }
; __device__ void attn_combine(const bf16_t* AP, const float* LSE, bf16_t* MIX) {
;     ...
;     for (int i = obid() * 512 + otid(); i < n; i += gridDim.x * 512) {
;         const int tok = i >> 7, ch = i & 127, h = ch >> 4;
;         const float l0 = LSE[((size_t)0 * T + tok) * 8 + h], l1 = LSE[((size_t)1 * T + tok) * 8 + h], l2 = LSE[((size_t)2 * T + tok) * 8 + h];
;         const float m = fmaxf(l0, fmaxf(l1, l2)); float w0 = __expf(l0 - m), w1 = __expf(l1 - m), w2 = __expf(l2 - m); const float rs = 1.0f / (w0 + w1 + w2); w0 *= rs; w1 *= rs; w2 *= rs;
;         const u32x4 a = *(const u32x4*)(AP + ((size_t)0 * T + tok) * 1024 + ch * 8), b = *(const u32x4*)(AP + ((size_t)1 * T + tok) * 1024 + ch * 8), c = *(const u32x4*)(AP + ((size_t)2 * T + tok) * 1024 + ch * 8);
;         u32x4 w;
; #pragma unroll
;         for (int e = 0; e < 4; ++e) w[e] = cvt_pk_bf16(w0 * bf_lo(a[e]) + w1 * bf_lo(b[e]) + w2 * bf_lo(c[e]), w0 * bf_hi(a[e]) + w1 * bf_hi(b[e]) + w2 * bf_hi(c[e]));
;         *(u32x4*)(MIX + (size_t)tok * DM + ch * 8) = w;
	v_lshlrev_b32_e32 v122, 16, v128
	v_and_b32_e32 v121, 0xffff0000, v128
	s_waitcnt vmcnt(8)
	v_and_b32_e32 v123, 0xffff0000, v132
	v_lshlrev_b32_e32 v120, 16, v132
	v_pk_mul_f32 v[122:123], v[116:117], v[122:123] op_sel:[1,0] op_sel_hi:[0,1]
	v_pk_fma_f32 v[120:121], v[116:117], v[120:121], v[122:123]
	v_lshlrev_b32_e32 v132, 16, v129
	v_pk_fma_f32 v[120:121], v[118:119], v[124:125], v[120:121] op_sel_hi:[0,1,1]
	v_cvt_pk_bf16_f32 v128, v120, v121
	v_lshlrev_b32_e32 v120, 16, v133
	v_and_b32_e32 v133, 0xffff0000, v133
	v_and_b32_e32 v121, 0xffff0000, v129
	v_pk_mul_f32 v[132:133], v[116:117], v[132:133] op_sel:[1,0] op_sel_hi:[0,1]
	v_pk_fma_f32 v[132:133], v[116:117], v[120:121], v[132:133]
	v_lshlrev_b32_e32 v120, 16, v114
	v_pk_fma_f32 v[132:133], v[118:119], v[112:113], v[132:133] op_sel_hi:[0,1,1]
	v_lshlrev_b32_e32 v112, 16, v130
	v_and_b32_e32 v113, 0xffff0000, v134
	v_cvt_pk_bf16_f32 v129, v132, v133
	v_lshlrev_b32_e32 v132, 16, v134
	v_and_b32_e32 v133, 0xffff0000, v130
	v_pk_mul_f32 v[112:113], v[116:117], v[112:113] op_sel:[1,0] op_sel_hi:[0,1]
	v_and_b32_e32 v121, 0xffff0000, v114
	v_pk_fma_f32 v[132:133], v[116:117], v[132:133], v[112:113]
	v_lshlrev_b32_e32 v134, 16, v131
	v_pk_fma_f32 v[132:133], v[118:119], v[120:121], v[132:133] op_sel_hi:[0,1,1]
	v_cvt_pk_bf16_f32 v130, v132, v133
	v_lshlrev_b32_e32 v132, 16, v135
	v_and_b32_e32 v135, 0xffff0000, v135
	v_and_b32_e32 v133, 0xffff0000, v131
	v_pk_mul_f32 v[134:135], v[116:117], v[134:135] op_sel:[1,0] op_sel_hi:[0,1]
	v_pk_fma_f32 v[132:133], v[116:117], v[132:133], v[134:135]
	v_lshlrev_b32_e32 v134, 16, v115
	v_and_b32_e32 v135, 0xffff0000, v115
	v_pk_fma_f32 v[132:133], v[118:119], v[134:135], v[132:133] op_sel_hi:[0,1,1]
	v_cvt_pk_bf16_f32 v131, v132, v133
	v_cmp_gt_i32_e32 vcc, 0x300000, v98
	s_nop 1
	s_and_saveexec_b64 s[12:13], vcc
	global_store_dwordx4 v[100:101], v[128:131], off
	s_mov_b64 exec, s[12:13]
	s_waitcnt vmcnt(6)
	v_max3_f32 v151, v142, v149, v150
	v_sub_f32_e32 v142, v142, v151
	v_mul_f32_e32 v142, 0x3fb8aa3b, v142
	v_exp_f32_e32 v163, v142
	v_sub_f32_e32 v142, v149, v151
	v_mul_f32_e32 v142, 0x3fb8aa3b, v142
	v_exp_f32_e32 v162, v142
	v_sub_f32_e32 v142, v150, v151
	v_mul_f32_e32 v142, 0x3fb8aa3b, v142
	v_exp_f32_e32 v149, v142
	v_add_f32_e32 v142, v163, v162
	s_waitcnt vmcnt(5)
	v_lshlrev_b32_e32 v170, 16, v158
	v_and_b32_e32 v171, 0xffff0000, v158
	v_add_f32_e32 v142, v149, v142
	v_div_scale_f32 v150, s[4:5], v142, v142, 1.0
	v_rcp_f32_e32 v151, v150
	v_lshlrev_b32_e32 v158, 16, v159
	v_and_b32_e32 v159, 0xffff0000, v159
	v_fma_f32 v152, -v150, v151, 1.0
	v_fmac_f32_e32 v151, v152, v151
	v_div_scale_f32 v152, vcc, 1.0, v142, 1.0
	v_mul_f32_e32 v153, v152, v151
	v_fma_f32 v156, -v150, v153, v152
	v_fmac_f32_e32 v153, v156, v151
	v_fma_f32 v150, -v150, v153, v152
	v_div_fmas_f32 v150, v150, v151, v153
	v_div_fixup_f32 v142, v150, v142, 1.0
	v_pk_mul_f32 v[162:163], v[162:163], v[142:143] op_sel_hi:[1,0]
	v_mul_f32_e32 v164, v149, v142
	v_lshlrev_b64 v[146:147], 12, v[146:147]
	v_lshl_add_u64 v[146:147], v[6:7], 0, v[146:147]
	s_waitcnt vmcnt(3)
	v_lshlrev_b32_e32 v168, 16, v174
	v_and_b32_e32 v167, 0xffff0000, v174
	s_waitcnt vmcnt(3)
	v_and_b32_e32 v169, 0xffff0000, v178
	v_lshlrev_b32_e32 v166, 16, v178
	v_pk_mul_f32 v[168:169], v[162:163], v[168:169] op_sel:[1,0] op_sel_hi:[0,1]
	v_pk_fma_f32 v[166:167], v[162:163], v[166:167], v[168:169]
	v_lshlrev_b32_e32 v178, 16, v175
	v_pk_fma_f32 v[166:167], v[164:165], v[170:171], v[166:167] op_sel_hi:[0,1,1]
	v_cvt_pk_bf16_f32 v174, v166, v167
	v_lshlrev_b32_e32 v166, 16, v179
	v_and_b32_e32 v179, 0xffff0000, v179
	v_and_b32_e32 v167, 0xffff0000, v175
	v_pk_mul_f32 v[178:179], v[162:163], v[178:179] op_sel:[1,0] op_sel_hi:[0,1]
	v_pk_fma_f32 v[178:179], v[162:163], v[166:167], v[178:179]
	v_lshlrev_b32_e32 v166, 16, v160
	v_pk_fma_f32 v[178:179], v[164:165], v[158:159], v[178:179] op_sel_hi:[0,1,1]
	v_lshlrev_b32_e32 v158, 16, v176
	v_and_b32_e32 v159, 0xffff0000, v180
	v_cvt_pk_bf16_f32 v175, v178, v179
	v_lshlrev_b32_e32 v178, 16, v180
	v_and_b32_e32 v179, 0xffff0000, v176
	v_pk_mul_f32 v[158:159], v[162:163], v[158:159] op_sel:[1,0] op_sel_hi:[0,1]
	v_and_b32_e32 v167, 0xffff0000, v160
	v_pk_fma_f32 v[178:179], v[162:163], v[178:179], v[158:159]
	v_lshlrev_b32_e32 v180, 16, v177
	v_pk_fma_f32 v[178:179], v[164:165], v[166:167], v[178:179] op_sel_hi:[0,1,1]
	v_cvt_pk_bf16_f32 v176, v178, v179
	v_lshlrev_b32_e32 v178, 16, v181
	v_and_b32_e32 v181, 0xffff0000, v181
	v_and_b32_e32 v179, 0xffff0000, v177
	v_pk_mul_f32 v[180:181], v[162:163], v[180:181] op_sel:[1,0] op_sel_hi:[0,1]
	v_pk_fma_f32 v[178:179], v[162:163], v[178:179], v[180:181]
	v_lshlrev_b32_e32 v180, 16, v161
	v_and_b32_e32 v181, 0xffff0000, v161
	v_pk_fma_f32 v[178:179], v[164:165], v[180:181], v[178:179] op_sel_hi:[0,1,1]
	v_cvt_pk_bf16_f32 v177, v178, v179
	v_cmp_gt_i32_e32 vcc, 0x300000, v144
	s_nop 1
	s_and_saveexec_b64 s[12:13], vcc
	global_store_dwordx4 v[146:147], v[174:177], off
	s_mov_b64 exec, s[12:13]
	s_mov_b32 s4, 0x2fffff
	v_cmp_lt_i32_e32 vcc, s4, v10
	s_nop 1
	s_or_b64 s[2:3], vcc, s[2:3]
	s_andn2_b64 exec, exec, s[2:3]
	s_cbranch_execnz .LBB0_297
